# attention K/V/bias prefetch: per-step address rebuild (15 VALU) replaced by three running pointers advanced by a scalar-selected stride
# baseline (speedup 1.0000x reference)
.LBB0_794:
	s_or_b64 exec, exec, s[8:9]
	s_add_i32 s0, 0, 0x9200
	s_mov_b64 s[6:7], src_shared_base
	s_cmp_lg_u32 s0, -1
	s_cselect_b32 s0, s0, 0
	s_cselect_b32 s6, s7, 0
	v_mov_b32_e32 v0, s0
	v_mov_b32_e32 v1, s6
	s_waitcnt lgkmcnt(0)
	s_barrier
	flat_load_dword v0, v[0:1] sc0 sc1
	s_waitcnt vmcnt(0)
	s_movk_i32 s0, 0x480
	s_mov_b64 s[8:9], -1
	s_waitcnt lgkmcnt(0)
	v_cmp_gt_i32_e64 s[6:7], s0, v0
	s_and_saveexec_b64 s[68:69], s[6:7]
	s_cbranch_execz .LBB0_789
	v_ashrrev_i32_e32 v1, 31, v0
	v_lshrrev_b32_e32 v1, 25, v1
	v_add_u32_e32 v1, v0, v1
	v_ashrrev_i32_e32 v8, 7, v1
	v_and_b32_e32 v1, 0xffffff80, v1
	v_sub_u32_e32 v0, v0, v1
	v_mov_b32_e32 v1, 11
	v_lshrrev_b16_sdwa v1, v1, sext(v0) dst_sel:DWORD dst_unused:UNUSED_PAD src0_sel:DWORD src1_sel:BYTE_0
	v_and_b32_e32 v1, 15, v1
	v_add_u16_e32 v1, v0, v1
	v_sub_u32_e32 v9, 8, v8
	v_ashrrev_i16_sdwa v2, v198, sext(v1) dst_sel:DWORD dst_unused:UNUSED_PAD src0_sel:DWORD src1_sel:BYTE_0
	s_movk_i32 s0, 0x810
	v_and_b32_e32 v1, 0xf0, v1
	v_mul_hi_i32_i24_sdwa v135, sext(v2), s0 dst_sel:DWORD dst_unused:UNUSED_PAD src0_sel:WORD_0 src1_sel:DWORD
	v_mul_i32_i24_sdwa v134, sext(v2), s0 dst_sel:DWORD dst_unused:UNUSED_PAD src0_sel:WORD_0 src1_sel:DWORD
	v_mul_hi_i32_i24_e32 v3, 0x2040, v0
	v_mul_i32_i24_e32 v2, 0x2040, v0
	v_lshlrev_b32_e32 v10, 8, v9
	v_sub_u16_e32 v4, v0, v1
	v_lshl_add_u64 v[140:141], s[62:63], 0, v[2:3]
	v_add_u32_e32 v164, v10, v156
	v_mov_b32_e32 v2, 6
	v_lshlrev_b32_sdwa v138, v2, sext(v4) dst_sel:DWORD dst_unused:UNUSED_PAD src0_sel:DWORD src1_sel:BYTE_0
	v_max_i32_e32 v6, 0xf0, v164
	v_ashrrev_i32_e32 v139, 31, v138
	v_add_u32_e32 v172, 0xffffff10, v6
	v_lshlrev_b64 v[2:3], 1, v[138:139]
	v_lshl_add_u64 v[6:7], v[134:135], 0, v[172:173]
	v_lshl_add_u64 v[4:5], v[120:121], 0, v[2:3]
	v_lshlrev_b64 v[6:7], 12, v[6:7]
	v_lshl_add_u64 v[6:7], v[4:5], 0, v[6:7]
	v_or_b32_e32 v139, 16, v164
	global_load_dwordx4 v[20:23], v[6:7], off
	global_load_dwordx4 v[24:27], v[6:7], off offset:64
	v_max_i32_e32 v6, 0xf0, v139
	v_add_u32_e32 v172, 0xffffff10, v6
	v_lshl_add_u64 v[6:7], v[134:135], 0, v[172:173]
	v_lshlrev_b64 v[6:7], 12, v[6:7]
	v_ashrrev_i32_e32 v1, 31, v0
	v_lshl_add_u64 v[4:5], v[4:5], 0, v[6:7]
	global_load_dwordx4 v[28:31], v[4:5], off
	global_load_dwordx4 v[32:35], v[4:5], off offset:64
	v_lshl_add_u64 v[4:5], v[134:135], 0, v[124:125]
	v_lshlrev_b64 v[0:1], 6, v[0:1]
	v_lshlrev_b64 v[4:5], 11, v[4:5]
	v_lshl_add_u64 v[0:1], v[0:1], 0, v[122:123]
	v_mov_b64_e32 v[6:7], s[88:89]
	v_lshl_add_u64 v[4:5], s[70:71], 0, v[4:5]
	v_mad_u64_u32 v[144:145], s[6:7], v0, s52, v[6:7]
	v_lshl_add_u64 v[4:5], v[4:5], 0, v[2:3]
	v_lshlrev_b32_e32 v142, 1, v126
	v_mov_b32_e32 v143, v173
	v_mad_i32_i24 v145, v1, s52, v145
	v_mov_b32_e32 v131, v173
	v_lshlrev_b32_e32 v165, 2, v9
	v_lshl_add_u64 v[4:5], v[4:5], 0, v[142:143]
	v_lshl_add_u64 v[0:1], v[144:145], 0, v[130:131]
	v_mov_b32_e32 v133, v173
	v_or_b32_e32 v166, 3, v165
	global_load_dwordx4 v[36:39], v[4:5], off
	global_load_dwordx4 v[40:43], v[0:1], off offset:-96
	v_lshl_add_u64 v[0:1], v[140:141], 0, v[132:133]
	global_load_dword v131, v[0:1], off offset:-192
	v_min_u32_e32 v0, 4, v166
	v_lshl_add_u32 v6, v0, 6, v201
	v_add_u32_e32 v0, v6, v122
	v_max_i32_e32 v172, 0, v0
	v_lshl_add_u64 v[0:1], v[134:135], 0, v[172:173]
	v_lshlrev_b64 v[0:1], 11, v[0:1]
	v_lshl_add_u64 v[0:1], s[70:71], 0, v[0:1]
	v_add_u32_e32 v4, v6, v126
	v_lshl_add_u64 v[0:1], v[0:1], 0, v[2:3]
	v_max_i32_e32 v4, 0, v4
	v_lshl_add_u64 v[0:1], v[0:1], 0, v[142:143]
	v_lshlrev_b32_e32 v172, 1, v4
	v_lshl_add_u64 v[4:5], v[144:145], 0, v[172:173]
	global_load_dwordx4 v[44:47], v[0:1], off
	global_load_dwordx4 v[48:51], v[4:5], off
	v_add_u32_e32 v0, v6, v154
	v_max_i32_e32 v0, 0, v0
	v_lshlrev_b32_e32 v172, 2, v0
	v_lshl_add_u64 v[0:1], v[140:141], 0, v[172:173]
	global_load_dword v167, v[0:1], off
	v_min_u32_e32 v0, 5, v166
	v_lshl_add_u32 v6, v0, 6, v201
	v_add_u32_e32 v0, v6, v122
	v_max_i32_e32 v172, 0, v0
	v_lshl_add_u64 v[0:1], v[134:135], 0, v[172:173]
	v_lshlrev_b64 v[0:1], 11, v[0:1]
	v_lshl_add_u64 v[0:1], s[70:71], 0, v[0:1]
	v_add_u32_e32 v4, v6, v126
	v_lshl_add_u64 v[0:1], v[0:1], 0, v[2:3]
	v_max_i32_e32 v4, 0, v4
	v_lshl_add_u64 v[0:1], v[0:1], 0, v[142:143]
	v_lshlrev_b32_e32 v172, 1, v4
	v_lshl_add_u64 v[4:5], v[144:145], 0, v[172:173]
	global_load_dwordx4 v[52:55], v[0:1], off
	global_load_dwordx4 v[56:59], v[4:5], off
	v_add_u32_e32 v0, v6, v154
	v_max_i32_e32 v0, 0, v0
	v_lshlrev_b32_e32 v172, 2, v0
	v_lshl_add_u64 v[0:1], v[140:141], 0, v[172:173]
	global_load_dword v169, v[0:1], off
	v_sub_u32_e32 v0, 0, v8
	v_or_b32_e32 v1, v10, v155
	v_lshl_add_u64 v[146:147], v[128:129], 0, v[2:3]
	v_lshlrev_b32_e32 v0, 8, v0
	v_mov_b32_e32 v2, v173
	v_mov_b32_e32 v3, v173
	v_add_u32_e32 v133, s85, v1
	v_sub_u32_e32 v168, 0, v0
	v_mov_b32_e32 v172, v173
	v_mov_b32_e32 v0, v173
	v_mov_b32_e32 v1, v173
	v_mov_b64_e32 v[6:7], v[2:3]
	v_mov_b64_e32 v[10:11], v[2:3]
	v_mov_b64_e32 v[14:15], v[2:3]
	v_mov_b64_e32 v[18:19], v[2:3]
	v_mov_b64_e32 v[62:63], v[2:3]
	v_mov_b64_e32 v[66:67], v[2:3]
	v_mov_b64_e32 v[70:71], v[2:3]
	s_mov_b32 s60, s87
	s_mov_b32 s84, 0
	v_or_b32_e32 v143, 16, v133
	v_mov_b32_e32 v148, 0xff800000
	s_mov_b64 s[34:35], 0
	v_mov_b32_e32 v170, 0
	s_mov_b32 s87, 0
	v_mov_b64_e32 v[4:5], v[0:1]
	v_mov_b64_e32 v[8:9], v[0:1]
	v_mov_b64_e32 v[12:13], v[0:1]
	v_mov_b64_e32 v[16:17], v[0:1]
	v_mov_b64_e32 v[60:61], v[0:1]
	v_mov_b64_e32 v[64:65], v[0:1]
	v_mov_b64_e32 v[68:69], v[0:1]
	v_mov_b64_e32 v[136:137], v[172:173]
	v_mov_b32_e32 v149, 0xff800000
	v_min_u32_e32 v228, 6, v166
	v_lshl_add_u32 v234, v228, 6, v201
	v_add_u32_e32 v228, v234, v122
	v_add_u32_e32 v230, v234, v126
	v_max_i32_e32 v172, 0, v228
	v_max_i32_e32 v230, 0, v230
	v_lshl_add_u64 v[228:229], v[134:135], 0, v[172:173]
	v_lshlrev_b32_e32 v172, 1, v230
	v_add_u32_e32 v234, v234, v154
	v_lshlrev_b64 v[228:229], 11, v[228:229]
	v_lshl_add_u64 v[230:231], v[144:145], 0, v[172:173]
	v_max_i32_e32 v172, 0, v234
	v_lshl_add_u64 v[228:229], v[146:147], 0, v[228:229]
	v_lshl_add_u64 v[232:233], v[172:173], 2, v[140:141]
	v_mov_b32_e32 v172, v173
	s_branch .LBB0_798

.LBB0_800:
	s_or_b64 exec, exec, s[6:7]
	s_waitcnt lgkmcnt(0)
	s_barrier
	global_load_dwordx4 v[36:39], v[228:229], off
	s_nop 0
	global_load_dwordx4 v[40:43], v[230:231], off
	s_add_i32 s0, s87, 3
	global_load_dword v131, v[232:233], off
	v_readfirstlane_b32 s100, v166
	s_add_i32 s101, s87, 6
	s_cmp_lt_u32 s101, s100
	s_cselect_b32 s100, 0x20000, 0
	s_mov_b32 s101, 0
	v_lshl_add_u64 v[228:229], s[100:101], 0, v[228:229]
	s_lshr_b32 s100, s100, 10
	v_lshl_add_u64 v[230:231], s[100:101], 0, v[230:231]
	s_lshl_b32 s100, s100, 1
	v_lshl_add_u64 v[232:233], s[100:101], 0, v[232:233]
	s_cmp_eq_u32 s87, 0
	s_cselect_b64 s[10:11], -1, 0
	v_cmp_ge_u32_e64 s[6:7], s0, v165
	v_cmp_lt_u32_e64 s[8:9], s0, v165
	s_or_b64 s[10:11], s[10:11], s[6:7]
	s_and_saveexec_b64 s[12:13], s[10:11]
	s_xor_b64 s[56:57], exec, s[12:13]
	s_cbranch_execz .LBB0_806
	s_and_saveexec_b64 s[10:11], s[6:7]
	v_add_u32_e32 v73, s84, v168
	v_add_u32_e32 v73, 0xfffff8c0, v73
	v_cmp_ge_i32_e64 s[6:7], s93, v73
	s_andn2_b64 s[8:9], s[8:9], exec
	s_and_b64 s[6:7], s[6:7], exec
	s_or_b64 s[8:9], s[8:9], s[6:7]
	s_or_b64 exec, exec, s[10:11]
	s_and_saveexec_b64 s[64:65], s[8:9]
	s_cbranch_execz .LBB0_805
	s_cmp_eq_u32 s87, 0
	s_cbranch_scc1 .Lattn_band1
	s_add_i32 s101, s87, 3
	v_readfirstlane_b32 s100, v165
	s_sub_i32 s100, s101, s100
	s_lshl_b32 s100, s100, 6
	s_add_i32 s100, s100, 63
	v_readfirstlane_b32 s101, v192
	s_lshr_b32 s101, s101, 6
	s_lshl_b32 s101, s101, 5
	s_cmp_le_i32 s100, s101
	s_cbranch_scc0 .Lattn_band1
	s_mov_b64 s[6:7], exec
	s_branch .Lattn_nb1

.LBB0_811:
	s_or_b64 exec, exec, s[6:7]
	s_waitcnt lgkmcnt(0)
	s_barrier
	global_load_dwordx4 v[44:47], v[228:229], off
	s_nop 0
	global_load_dwordx4 v[48:51], v[230:231], off
	s_add_i32 s6, s87, 4
	global_load_dword v167, v[232:233], off
	v_readfirstlane_b32 s100, v166
	s_add_i32 s101, s87, 7
	s_cmp_lt_u32 s101, s100
	s_cselect_b32 s100, 0x20000, 0
	s_mov_b32 s101, 0
	v_lshl_add_u64 v[228:229], s[100:101], 0, v[228:229]
	s_lshr_b32 s100, s100, 10
	v_lshl_add_u64 v[230:231], s[100:101], 0, v[230:231]
	s_lshl_b32 s100, s100, 1
	v_lshl_add_u64 v[232:233], s[100:101], 0, v[232:233]
	v_cmp_ge_u32_e64 s[6:7], s6, v165
	s_and_saveexec_b64 s[8:9], s[6:7]
	s_xor_b64 s[64:65], exec, s[8:9]
	s_cbranch_execz .LBB0_815
	v_add_u32_e32 v73, s84, v168
	v_add_u32_e32 v73, 0xfffff900, v73
	v_cmp_ge_i32_e64 s[6:7], s93, v73
	s_and_saveexec_b64 s[72:73], s[6:7]
	s_cbranch_execz .LBB0_814
	s_add_i32 s101, s87, 4
	v_readfirstlane_b32 s100, v165
	s_sub_i32 s100, s101, s100
	s_lshl_b32 s100, s100, 6
	s_add_i32 s100, s100, 63
	v_readfirstlane_b32 s101, v192
	s_lshr_b32 s101, s101, 6
	s_lshl_b32 s101, s101, 5
	s_cmp_le_i32 s100, s101
	s_cbranch_scc0 .Lattn_band2
	s_mov_b64 s[6:7], exec
	s_branch .Lattn_nb2

.LBB0_821:
	s_or_b64 exec, exec, s[6:7]
	s_waitcnt lgkmcnt(0)
	s_barrier
	global_load_dwordx4 v[52:55], v[228:229], off
	s_nop 0
	global_load_dwordx4 v[56:59], v[230:231], off
	v_cmp_ge_u32_e64 s[6:7], s8, v165
	global_load_dword v169, v[232:233], off
	v_readfirstlane_b32 s100, v166
	s_add_i32 s101, s87, 8
	s_cmp_lt_u32 s101, s100
	s_cselect_b32 s100, 0x20000, 0
	s_mov_b32 s101, 0
	v_lshl_add_u64 v[228:229], s[100:101], 0, v[228:229]
	s_lshr_b32 s100, s100, 10
	v_lshl_add_u64 v[230:231], s[100:101], 0, v[230:231]
	s_lshl_b32 s100, s100, 1
	v_lshl_add_u64 v[232:233], s[100:101], 0, v[232:233]
	s_and_saveexec_b64 s[8:9], s[6:7]
	s_xor_b64 s[64:65], exec, s[8:9]
	s_cbranch_execz .LBB0_825
	v_add_u32_e32 v73, s84, v168
	v_add_u32_e32 v73, 0xfffff940, v73
	v_cmp_ge_i32_e64 s[6:7], s93, v73
	s_and_saveexec_b64 s[72:73], s[6:7]
	s_cbranch_execz .LBB0_824
	s_add_i32 s101, s87, 5
	v_readfirstlane_b32 s100, v165
	s_sub_i32 s100, s101, s100
	s_lshl_b32 s100, s100, 6
	s_add_i32 s100, s100, 63
	v_readfirstlane_b32 s101, v192
	s_lshr_b32 s101, s101, 6
	s_lshl_b32 s101, s101, 5
	s_cmp_le_i32 s100, s101
	s_cbranch_scc0 .Lattn_band3
	s_mov_b64 s[6:7], exec
	s_branch .Lattn_nb3
